# grid barrier release flattened: every workgroup polls the cross-XCC release word directly, the XCC leaders no longer relay
# baseline (speedup 1.0000x reference)
; __device__ __forceinline__ unsigned xb_ld(unsigned* p)              { return __hip_atomic_load(p, __ATOMIC_RELAXED, __HIP_MEMORY_SCOPE_AGENT); }
; __device__ __forceinline__ unsigned xb_add(unsigned* p, unsigned v) { return __hip_atomic_fetch_add(p, v, __ATOMIC_RELAXED, __HIP_MEMORY_SCOPE_AGENT); }
; #define XB_SPIN(cond, bar) do { unsigned _sp = 0; while (cond) { __builtin_amdgcn_s_sleep(1); \
;     if ((++_sp & 255u) == 0u) { if (xb_ld(&(bar)[XB_TMO])) break; if (_sp > XB_SPIN_CAP) { atomicAdd(&(bar)[XB_TMO], 1u); break; } } } } while (0)
; __device__ __forceinline__ void xcd_barrier(const XcdBarrier& b) {
;     asm volatile("s_waitcnt vmcnt(0)" ::: "memory");
;     __syncthreads();
;     if (threadIdx.x == 0) {
;         unsigned* bar = b.bar;
;         __builtin_amdgcn_s_waitcnt(0);
;         unsigned nloc = b.st[0], nx = b.st[1];
;         if (nloc == 0u) { xcd_barrier_complete(bar, b.x, nloc, nx); b.st[0] = nloc; b.st[1] = nx; }
;         const unsigned old = xb_add(&bar[XB_XSUB(b.x)], 1u);
;         const unsigned gen = old / nloc;
;         if (old + 1u == (gen + 1u) * nloc) {
;             __builtin_amdgcn_fence(__ATOMIC_RELEASE, "agent");
;             asm volatile("s_waitcnt vmcnt(0)" ::: "memory");
;             const unsigned og = xb_add(&bar[XB_TOP], 1u);
;             const unsigned tg = og / nx;
;             if (og + 1u == (tg + 1u) * nx) xb_add(&bar[XB_TOPGEN], 1u);
;             else XB_SPIN(xb_ld(&bar[XB_TOPGEN]) == tg, bar);
;             __builtin_amdgcn_fence(__ATOMIC_ACQUIRE, "agent");
;             xb_add(&bar[XB_XGEN(b.x)], 1u);
;             asm volatile("s_waitcnt vmcnt(0)" ::: "memory");
;         } else {
;             XB_SPIN(xb_ld(&bar[XB_XGEN(b.x)]) == gen, bar);
;             __builtin_amdgcn_fence(__ATOMIC_ACQUIRE, "agent");
;             asm volatile("s_waitcnt vmcnt(0)" ::: "memory");
.LBB0_356:
	s_or_b64 exec, exec, s[12:13]
	v_cvt_f32_u32_e32 v5, v3
	s_waitcnt vmcnt(0)
	v_readfirstlane_b32 s4, v4
	v_sub_u32_e32 v4, 0, v3
	v_rcp_iflag_f32_e32 v5, v5
	v_add_u32_e32 v6, s4, v0
	v_mul_f32_e32 v5, 0x4f7ffffe, v5
	v_cvt_u32_f32_e32 v5, v5
	v_mul_lo_u32 v0, v4, v5
	v_mul_hi_u32 v0, v5, v0
	v_add_u32_e32 v0, v5, v0
	v_mul_hi_u32 v0, v6, v0
	v_mul_lo_u32 v4, v0, v3
	v_sub_u32_e32 v4, v6, v4
	v_add_u32_e32 v5, 1, v0
	v_cmp_ge_u32_e32 vcc, v4, v3
	s_nop 1
	v_cndmask_b32_e32 v0, v0, v5, vcc
	v_sub_u32_e32 v5, v4, v3
	v_cndmask_b32_e32 v4, v4, v5, vcc
	v_add_u32_e32 v5, 1, v0
	v_cmp_ge_u32_e32 vcc, v4, v3
	v_add_u32_e32 v4, 1, v6
	s_nop 0
	v_cndmask_b32_e32 v0, v0, v5, vcc
	v_mul_lo_u32 v5, v3, v0
	v_add_u32_e32 v3, v5, v3
	v_cmp_ne_u32_e32 vcc, v4, v3
	s_and_saveexec_b64 s[4:5], vcc
	s_xor_b64 s[4:5], exec, s[4:5]
	s_cbranch_execz .LBB0_370
	s_add_u32 s14, s10, 0x3500
	s_addc_u32 s15, s11, 0
	s_waitcnt lgkmcnt(0)
	global_load_dword v2, v1, s[14:15] sc1
	s_waitcnt vmcnt(0)
	v_cmp_eq_u32_e32 vcc, v2, v0
	s_and_saveexec_b64 s[12:13], vcc
	s_cbranch_execz .LBB0_369
	s_mov_b32 s20, 1
	s_mov_b64 s[54:55], 0
	s_branch .LBB0_360

; __device__ __forceinline__ unsigned xb_ld(unsigned* p)              { return __hip_atomic_load(p, __ATOMIC_RELAXED, __HIP_MEMORY_SCOPE_AGENT); }
; __device__ __forceinline__ unsigned xb_add(unsigned* p, unsigned v) { return __hip_atomic_fetch_add(p, v, __ATOMIC_RELAXED, __HIP_MEMORY_SCOPE_AGENT); }
; #define XB_SPIN(cond, bar) do { unsigned _sp = 0; while (cond) { __builtin_amdgcn_s_sleep(1); \
;     if ((++_sp & 255u) == 0u) { if (xb_ld(&(bar)[XB_TMO])) break; if (_sp > XB_SPIN_CAP) { atomicAdd(&(bar)[XB_TMO], 1u); break; } } } } while (0)
; __device__ __forceinline__ void xcd_barrier(const XcdBarrier& b) {
;     ...
;         const unsigned old = xb_add(&bar[XB_XSUB(b.x)], 1u);
;         const unsigned gen = old / nloc;
;         if (old + 1u == (gen + 1u) * nloc) {
;             __builtin_amdgcn_fence(__ATOMIC_RELEASE, "agent");
;             asm volatile("s_waitcnt vmcnt(0)" ::: "memory");
;             const unsigned og = xb_add(&bar[XB_TOP], 1u);
;             const unsigned tg = og / nx;
;             if (og + 1u == (tg + 1u) * nx) xb_add(&bar[XB_TOPGEN], 1u);
;             else XB_SPIN(xb_ld(&bar[XB_TOPGEN]) == tg, bar);
;             __builtin_amdgcn_fence(__ATOMIC_ACQUIRE, "agent");
;             xb_add(&bar[XB_XGEN(b.x)], 1u);
;             asm volatile("s_waitcnt vmcnt(0)" ::: "memory");
.LBB0_387:
	s_or_b64 exec, exec, s[4:5]
	s_mov_b64 s[4:5], exec
	v_mbcnt_lo_u32_b32 v0, s4, 0
	v_mbcnt_hi_u32_b32 v0, s5, v0
	v_cmp_eq_u32_e32 vcc, 0, v0
	s_waitcnt vmcnt(0)
	buffer_inv sc1
	s_and_saveexec_b64 s[12:13], vcc
	s_cbranch_execz .LBB0_389
.LBB0_389:
	s_or_b64 exec, exec, s[12:13]
	s_waitcnt vmcnt(0)

; __device__ __forceinline__ unsigned xb_ld(unsigned* p)              { return __hip_atomic_load(p, __ATOMIC_RELAXED, __HIP_MEMORY_SCOPE_AGENT); }
; __device__ __forceinline__ unsigned xb_add(unsigned* p, unsigned v) { return __hip_atomic_fetch_add(p, v, __ATOMIC_RELAXED, __HIP_MEMORY_SCOPE_AGENT); }
; #define XB_SPIN(cond, bar) do { unsigned _sp = 0; while (cond) { __builtin_amdgcn_s_sleep(1); \
;     if ((++_sp & 255u) == 0u) { if (xb_ld(&(bar)[XB_TMO])) break; if (_sp > XB_SPIN_CAP) { atomicAdd(&(bar)[XB_TMO], 1u); break; } } } } while (0)
; __device__ __forceinline__ void xcd_barrier(const XcdBarrier& b) {
;     asm volatile("s_waitcnt vmcnt(0)" ::: "memory");
;     __syncthreads();
;     if (threadIdx.x == 0) {
;         unsigned* bar = b.bar;
;         __builtin_amdgcn_s_waitcnt(0);
;         unsigned nloc = b.st[0], nx = b.st[1];
;         if (nloc == 0u) { xcd_barrier_complete(bar, b.x, nloc, nx); b.st[0] = nloc; b.st[1] = nx; }
;         const unsigned old = xb_add(&bar[XB_XSUB(b.x)], 1u);
;         const unsigned gen = old / nloc;
;         if (old + 1u == (gen + 1u) * nloc) {
;             __builtin_amdgcn_fence(__ATOMIC_RELEASE, "agent");
;             asm volatile("s_waitcnt vmcnt(0)" ::: "memory");
;             const unsigned og = xb_add(&bar[XB_TOP], 1u);
;             const unsigned tg = og / nx;
;             if (og + 1u == (tg + 1u) * nx) xb_add(&bar[XB_TOPGEN], 1u);
;             else XB_SPIN(xb_ld(&bar[XB_TOPGEN]) == tg, bar);
;             __builtin_amdgcn_fence(__ATOMIC_ACQUIRE, "agent");
;             xb_add(&bar[XB_XGEN(b.x)], 1u);
;             asm volatile("s_waitcnt vmcnt(0)" ::: "memory");
;         } else {
;             XB_SPIN(xb_ld(&bar[XB_XGEN(b.x)]) == gen, bar);
;             __builtin_amdgcn_fence(__ATOMIC_ACQUIRE, "agent");
;             asm volatile("s_waitcnt vmcnt(0)" ::: "memory");
.LBB0_892:
	s_or_b64 exec, exec, s[10:11]
	v_cvt_f32_u32_e32 v5, v3
	s_waitcnt vmcnt(0)
	v_readfirstlane_b32 s4, v4
	v_sub_u32_e32 v4, 0, v3
	v_rcp_iflag_f32_e32 v5, v5
	v_add_u32_e32 v6, s4, v0
	v_mul_f32_e32 v5, 0x4f7ffffe, v5
	v_cvt_u32_f32_e32 v5, v5
	v_mul_lo_u32 v0, v4, v5
	v_mul_hi_u32 v0, v5, v0
	v_add_u32_e32 v0, v5, v0
	v_mul_hi_u32 v0, v6, v0
	v_mul_lo_u32 v4, v0, v3
	v_sub_u32_e32 v4, v6, v4
	v_add_u32_e32 v5, 1, v0
	v_cmp_ge_u32_e32 vcc, v4, v3
	s_nop 1
	v_cndmask_b32_e32 v0, v0, v5, vcc
	v_sub_u32_e32 v5, v4, v3
	v_cndmask_b32_e32 v4, v4, v5, vcc
	v_add_u32_e32 v5, 1, v0
	v_cmp_ge_u32_e32 vcc, v4, v3
	v_add_u32_e32 v4, 1, v6
	s_nop 0
	v_cndmask_b32_e32 v0, v0, v5, vcc
	v_mul_lo_u32 v5, v3, v0
	v_add_u32_e32 v3, v5, v3
	v_cmp_ne_u32_e32 vcc, v4, v3
	s_and_saveexec_b64 s[4:5], vcc
	s_xor_b64 s[4:5], exec, s[4:5]
	s_cbranch_execz .LBB0_906
	s_add_u32 s12, s8, 0x3500
	s_addc_u32 s13, s9, 0
	s_waitcnt lgkmcnt(0)
	global_load_dword v2, v1, s[12:13] sc1
	s_waitcnt vmcnt(0)
	v_cmp_eq_u32_e32 vcc, v2, v0
	s_and_saveexec_b64 s[10:11], vcc
	s_cbranch_execz .LBB0_905
	s_mov_b32 s20, 1
	s_mov_b64 s[14:15], 0
	s_branch .LBB0_896

; __device__ __forceinline__ unsigned xb_ld(unsigned* p)              { return __hip_atomic_load(p, __ATOMIC_RELAXED, __HIP_MEMORY_SCOPE_AGENT); }
; __device__ __forceinline__ unsigned xb_add(unsigned* p, unsigned v) { return __hip_atomic_fetch_add(p, v, __ATOMIC_RELAXED, __HIP_MEMORY_SCOPE_AGENT); }
; #define XB_SPIN(cond, bar) do { unsigned _sp = 0; while (cond) { __builtin_amdgcn_s_sleep(1); \
;     if ((++_sp & 255u) == 0u) { if (xb_ld(&(bar)[XB_TMO])) break; if (_sp > XB_SPIN_CAP) { atomicAdd(&(bar)[XB_TMO], 1u); break; } } } } while (0)
; __device__ __forceinline__ void xcd_barrier(const XcdBarrier& b) {
;     ...
;         const unsigned old = xb_add(&bar[XB_XSUB(b.x)], 1u);
;         const unsigned gen = old / nloc;
;         if (old + 1u == (gen + 1u) * nloc) {
;             __builtin_amdgcn_fence(__ATOMIC_RELEASE, "agent");
;             asm volatile("s_waitcnt vmcnt(0)" ::: "memory");
;             const unsigned og = xb_add(&bar[XB_TOP], 1u);
;             const unsigned tg = og / nx;
;             if (og + 1u == (tg + 1u) * nx) xb_add(&bar[XB_TOPGEN], 1u);
;             else XB_SPIN(xb_ld(&bar[XB_TOPGEN]) == tg, bar);
;             __builtin_amdgcn_fence(__ATOMIC_ACQUIRE, "agent");
;             xb_add(&bar[XB_XGEN(b.x)], 1u);
;             asm volatile("s_waitcnt vmcnt(0)" ::: "memory");
.LBB0_923:
	s_or_b64 exec, exec, s[4:5]
	s_mov_b64 s[4:5], exec
	v_mbcnt_lo_u32_b32 v0, s4, 0
	v_mbcnt_hi_u32_b32 v0, s5, v0
	v_cmp_eq_u32_e32 vcc, 0, v0
	s_waitcnt vmcnt(0)
	buffer_inv sc1
	s_and_saveexec_b64 s[10:11], vcc
	s_cbranch_execz .LBB0_7
	s_branch .LBB0_7
